# v13 + uq/ukv EpiGen heads: the 8 exec-masked serialized ssq loads per tile issued up front into dead VGPRs (same mask), each load+vmcnt(0) becomes vmcnt(7-r)+copies
# speedup vs baseline: 1.0101x; 1.0092x over previous
; __device__ __forceinline__ float row_ssq(const float* part, int pitch, int n4, int row, int fq) {
;     f32x4 v = (f32x4){0.f, 0.f, 0.f, 0.f};
;     if (fq < n4) v = *(const f32x4*)(part + (size_t)row * pitch + 4 * fq);
;     float s = (v[0] + v[1]) + (v[2] + v[3]);
;     s += __shfl_xor(s, 16); s += __shfl_xor(s, 32);
;     return s;
; }
;     __device__ __forceinline__ void operator()(const f32x4 (&acc)[2][2][4][2], const Unit& u, int wr, int wc, int fr, int fq) const {
;         const int row0 = u.pm * BM + wr * 64 + fr;
;         float rsv[2][4];
; #pragma unroll
;         for (int ai = 0; ai < 2; ++ai)
; #pragma unroll
;             for (int m = 0; m < 4; ++m) rsv[ai][m] = ssq_in ? rsqrtf(row_ssq(ssq_in, in_pitch, in_n4, row0 + ai * HALF + m * 16, fq) * inv_k + EPS) : 1.f;
.LBB0_568:
	v_lshl_add_u32 v154, s40, 8, v145
	v_mov_b32_e32 v130, 0
	v_ashrrev_i32_e32 v155, 31, v154
	s_and_saveexec_b64 s[98:99], s[44:45]
	v_lshlrev_b64 v[234:235], 6, v[154:155]
	v_lshl_add_u64 v[234:235], v[146:147], 0, v[234:235]
	global_load_dwordx4 v[194:197], v[234:235], off
	global_load_dwordx4 v[198:201], v[234:235], off offset:1024
	global_load_dwordx4 v[206:209], v[234:235], off offset:2048
	global_load_dwordx4 v[210:213], v[234:235], off offset:3072
	v_add_co_u32_e32 v234, vcc, 0x2000, v234
	s_nop 1
	v_addc_co_u32_e32 v235, vcc, 0, v235, vcc
	global_load_dwordx4 v[214:217], v[234:235], off
	global_load_dwordx4 v[218:221], v[234:235], off offset:1024
	global_load_dwordx4 v[226:229], v[234:235], off offset:2048
	global_load_dwordx4 v[230:233], v[234:235], off offset:3072
	s_or_b64 exec, exec, s[98:99]
	v_mov_b32_e32 v132, 0
	v_mov_b32_e32 v156, 0
	v_mov_b32_e32 v157, 0
	v_mov_b32_e32 v133, 0
	s_and_saveexec_b64 s[18:19], s[44:45]
	s_cbranch_execz .LBB0_570
	v_lshlrev_b64 v[132:133], 6, v[154:155]
	v_lshl_add_u64 v[132:133], v[146:147], 0, v[132:133]
	s_waitcnt vmcnt(7)
	v_mov_b32_e32 v132, v194
	v_mov_b32_e32 v133, v195
	v_mov_b32_e32 v134, v196
	v_mov_b32_e32 v135, v197
	v_mov_b32_e32 v156, v133
	v_mov_b32_e32 v157, v134
	v_mov_b32_e32 v133, v135
.LBB0_570:
	s_or_b64 exec, exec, s[18:19]
	v_pk_add_f32 v[132:133], v[156:157], v[132:133]
	v_xor_b32_e32 v131, 16, v241
	v_add_f32_e32 v0, v132, v133
	v_and_b32_e32 v132, 64, v241
	v_add_u32_e32 v132, 64, v132
	v_cmp_lt_i32_e32 vcc, v131, v132
	v_or_b32_e32 v162, 16, v154
	v_mov_b32_e32 v134, 0
	v_cndmask_b32_e32 v131, v241, v131, vcc
	v_lshlrev_b32_e32 v176, 2, v131
	ds_bpermute_b32 v131, v176, v0
	v_mov_b32_e32 v135, 0
	s_waitcnt lgkmcnt(0)
	v_add_f32_e32 v177, v0, v131
	v_xor_b32_e32 v0, 32, v241
	v_cmp_lt_i32_e32 vcc, v0, v132
	v_mov_b32_e32 v131, 0
	s_nop 0
	v_cndmask_b32_e32 v0, v241, v0, vcc
	v_lshlrev_b32_e32 v168, 2, v0
	ds_bpermute_b32 v178, v168, v177
	s_and_saveexec_b64 s[18:19], s[44:45]
	s_cbranch_execz .LBB0_572
	v_ashrrev_i32_e32 v163, 31, v162
	v_lshlrev_b64 v[130:131], 6, v[162:163]
	v_lshl_add_u64 v[130:131], v[146:147], 0, v[130:131]
	s_waitcnt vmcnt(6)
	v_mov_b32_e32 v130, v198
	v_mov_b32_e32 v131, v199
	v_mov_b32_e32 v132, v200
	v_mov_b32_e32 v133, v201
	v_mov_b32_e32 v134, v131
	v_mov_b32_e32 v135, v132
	v_mov_b32_e32 v131, v133
.LBB0_572:
	s_or_b64 exec, exec, s[18:19]
	v_pk_add_f32 v[130:131], v[134:135], v[130:131]
	v_or_b32_e32 v160, 32, v154
	v_add_f32_e32 v0, v130, v131
	ds_bpermute_b32 v131, v176, v0
	v_mov_b32_e32 v130, 0
	v_mov_b32_e32 v132, 0
	v_mov_b32_e32 v156, 0
	v_mov_b32_e32 v157, 0
	s_waitcnt lgkmcnt(0)
	v_add_f32_e32 v0, v0, v131
	ds_bpermute_b32 v175, v168, v0
	v_mov_b32_e32 v133, 0
	s_and_saveexec_b64 s[18:19], s[44:45]
	s_cbranch_execz .LBB0_574
	v_ashrrev_i32_e32 v161, 31, v160
	v_lshlrev_b64 v[132:133], 6, v[160:161]
	v_lshl_add_u64 v[132:133], v[146:147], 0, v[132:133]
	s_waitcnt vmcnt(5)
	v_mov_b32_e32 v132, v206
	v_mov_b32_e32 v133, v207
	v_mov_b32_e32 v134, v208
	v_mov_b32_e32 v135, v209
	v_mov_b32_e32 v156, v133
	v_mov_b32_e32 v157, v134
	v_mov_b32_e32 v133, v135
.LBB0_574:
	s_or_b64 exec, exec, s[18:19]
	v_pk_add_f32 v[132:133], v[156:157], v[132:133]
	v_or_b32_e32 v158, 48, v154
	v_add_f32_e32 v131, v132, v133
	ds_bpermute_b32 v132, v176, v131
	v_mov_b32_e32 v134, 0
	v_mov_b32_e32 v135, 0
	s_waitcnt lgkmcnt(0)
	v_add_f32_e32 v173, v131, v132
	ds_bpermute_b32 v174, v168, v173
	v_mov_b32_e32 v131, 0
	s_and_saveexec_b64 s[18:19], s[44:45]
	s_cbranch_execz .LBB0_576
	v_ashrrev_i32_e32 v159, 31, v158
	v_lshlrev_b64 v[130:131], 6, v[158:159]
	v_lshl_add_u64 v[130:131], v[146:147], 0, v[130:131]
	s_waitcnt vmcnt(4)
	v_mov_b32_e32 v130, v210
	v_mov_b32_e32 v131, v211
	v_mov_b32_e32 v132, v212
	v_mov_b32_e32 v133, v213
	v_mov_b32_e32 v134, v131
	v_mov_b32_e32 v135, v132
	v_mov_b32_e32 v131, v133
.LBB0_576:
	s_or_b64 exec, exec, s[18:19]
	v_pk_add_f32 v[130:131], v[134:135], v[130:131]
	v_add_u32_e32 v156, 0x80, v154
	v_add_f32_e32 v130, v130, v131
	ds_bpermute_b32 v131, v176, v130
	v_mov_b32_e32 v132, 0
	v_mov_b32_e32 v164, 0
	v_mov_b32_e32 v165, 0
	v_mov_b32_e32 v133, 0
	s_waitcnt lgkmcnt(0)
	v_add_f32_e32 v171, v130, v131
	ds_bpermute_b32 v172, v168, v171
	v_mov_b32_e32 v130, 0
	s_and_saveexec_b64 s[18:19], s[44:45]
	s_cbranch_execz .LBB0_578
	v_ashrrev_i32_e32 v157, 31, v156
	v_lshlrev_b64 v[132:133], 6, v[156:157]
	v_lshl_add_u64 v[132:133], v[146:147], 0, v[132:133]
	s_waitcnt vmcnt(3)
	v_mov_b32_e32 v132, v214
	v_mov_b32_e32 v133, v215
	v_mov_b32_e32 v134, v216
	v_mov_b32_e32 v135, v217
	v_mov_b32_e32 v164, v133
	v_mov_b32_e32 v165, v134
	v_mov_b32_e32 v133, v135
.LBB0_578:
	s_or_b64 exec, exec, s[18:19]
	v_pk_add_f32 v[132:133], v[164:165], v[132:133]
	v_mov_b32_e32 v134, 0
	v_add_f32_e32 v131, v132, v133
	ds_bpermute_b32 v132, v176, v131
	v_mov_b32_e32 v135, 0
	s_waitcnt lgkmcnt(0)
	v_add_f32_e32 v169, v131, v132
	ds_bpermute_b32 v170, v168, v169
	v_mov_b32_e32 v131, 0
	s_and_saveexec_b64 s[18:19], s[44:45]
	s_cbranch_execz .LBB0_580
	v_lshlrev_b64 v[130:131], 6, v[154:155]
	v_lshl_add_u64 v[130:131], v[146:147], 0, v[130:131]
	v_add_co_u32_e32 v130, vcc, 0x2000, v130
	s_nop 1
	v_addc_co_u32_e32 v131, vcc, 0, v131, vcc
	s_waitcnt vmcnt(2)
	v_mov_b32_e32 v130, v218
	v_mov_b32_e32 v131, v219
	v_mov_b32_e32 v132, v220
	v_mov_b32_e32 v133, v221
	v_mov_b32_e32 v134, v131
	v_mov_b32_e32 v135, v132
	v_mov_b32_e32 v131, v133
.LBB0_580:
	s_or_b64 exec, exec, s[18:19]
	v_pk_add_f32 v[130:131], v[134:135], v[130:131]
	v_mov_b32_e32 v132, 0
	v_add_f32_e32 v130, v130, v131
	ds_bpermute_b32 v131, v176, v130
	v_mov_b32_e32 v164, 0
	v_mov_b32_e32 v165, 0
	v_mov_b32_e32 v133, 0
	s_waitcnt lgkmcnt(0)
	v_add_f32_e32 v161, v130, v131
	ds_bpermute_b32 v163, v168, v161
	v_mov_b32_e32 v130, 0
	s_and_saveexec_b64 s[18:19], s[44:45]
	s_cbranch_execz .LBB0_582
	v_lshlrev_b64 v[132:133], 6, v[154:155]
	v_lshl_add_u64 v[132:133], v[146:147], 0, v[132:133]
	v_add_co_u32_e32 v132, vcc, 0x2000, v132
	s_nop 1
	v_addc_co_u32_e32 v133, vcc, 0, v133, vcc
	s_waitcnt vmcnt(1)
	v_mov_b32_e32 v132, v226
	v_mov_b32_e32 v133, v227
	v_mov_b32_e32 v134, v228
	v_mov_b32_e32 v135, v229
	v_mov_b32_e32 v164, v133
	v_mov_b32_e32 v165, v134
	v_mov_b32_e32 v133, v135
.LBB0_582:
	s_or_b64 exec, exec, s[18:19]
	v_pk_add_f32 v[132:133], v[164:165], v[132:133]
	v_mov_b32_e32 v134, 0
	v_add_f32_e32 v131, v132, v133
	ds_bpermute_b32 v132, v176, v131
	v_mov_b32_e32 v135, 0
	s_waitcnt lgkmcnt(0)
	v_add_f32_e32 v157, v131, v132
	ds_bpermute_b32 v159, v168, v157
	v_mov_b32_e32 v131, 0
	s_and_saveexec_b64 s[18:19], s[44:45]
	s_cbranch_execz .LBB0_584
	v_lshlrev_b64 v[130:131], 6, v[154:155]
	v_lshl_add_u64 v[130:131], v[146:147], 0, v[130:131]
	v_add_co_u32_e32 v130, vcc, 0x2000, v130
	s_nop 1
	v_addc_co_u32_e32 v131, vcc, 0, v131, vcc
	s_waitcnt vmcnt(0)
	v_mov_b32_e32 v130, v230
	v_mov_b32_e32 v131, v231
	v_mov_b32_e32 v132, v232
	v_mov_b32_e32 v133, v233
	v_mov_b32_e32 v134, v131
	v_mov_b32_e32 v135, v132
	v_mov_b32_e32 v131, v133

; __device__ __forceinline__ float row_ssq(const float* part, int pitch, int n4, int row, int fq) {
;     f32x4 v = (f32x4){0.f, 0.f, 0.f, 0.f};
;     if (fq < n4) v = *(const f32x4*)(part + (size_t)row * pitch + 4 * fq);
;     float s = (v[0] + v[1]) + (v[2] + v[3]);
;     s += __shfl_xor(s, 16); s += __shfl_xor(s, 32);
;     return s;
; }
;     __device__ __forceinline__ void operator()(const f32x4 (&acc)[2][2][4][2], const Unit& u, int wr, int wc, int fr, int fq) const {
;         const int row0 = u.pm * BM + wr * 64 + fr;
;         float rsv[2][4];
; #pragma unroll
;         for (int ai = 0; ai < 2; ++ai)
; #pragma unroll
;             for (int m = 0; m < 4; ++m) rsv[ai][m] = ssq_in ? rsqrtf(row_ssq(ssq_in, in_pitch, in_n4, row0 + ai * HALF + m * 16, fq) * inv_k + EPS) : 1.f;
.LBB0_638:
	v_lshl_add_u32 v146, s53, 8, v159
	v_mov_b32_e32 v130, 0
	v_ashrrev_i32_e32 v147, 31, v146
	s_and_saveexec_b64 s[98:99], s[44:45]
	v_lshlrev_b64 v[234:235], 5, v[146:147]
	v_lshl_add_u64 v[234:235], v[144:145], 0, v[234:235]
	global_load_dwordx4 v[194:197], v[234:235], off
	global_load_dwordx4 v[198:201], v[234:235], off offset:512
	global_load_dwordx4 v[206:209], v[234:235], off offset:1024
	global_load_dwordx4 v[210:213], v[234:235], off offset:1536
	v_add_co_u32_e32 v234, vcc, 0x1000, v234
	s_nop 1
	v_addc_co_u32_e32 v235, vcc, 0, v235, vcc
	global_load_dwordx4 v[214:217], v[234:235], off
	global_load_dwordx4 v[218:221], v[234:235], off offset:512
	global_load_dwordx4 v[226:229], v[234:235], off offset:1024
	global_load_dwordx4 v[230:233], v[234:235], off offset:1536
	s_or_b64 exec, exec, s[98:99]
	v_mov_b32_e32 v132, 0
	v_mov_b32_e32 v148, 0
	v_mov_b32_e32 v149, 0
	v_mov_b32_e32 v133, 0
	s_and_saveexec_b64 s[0:1], s[44:45]
	s_cbranch_execz .LBB0_640
	v_lshlrev_b64 v[132:133], 5, v[146:147]
	v_lshl_add_u64 v[132:133], v[144:145], 0, v[132:133]
	s_waitcnt vmcnt(7)
	v_mov_b32_e32 v132, v194
	v_mov_b32_e32 v133, v195
	v_mov_b32_e32 v134, v196
	v_mov_b32_e32 v135, v197
	v_mov_b32_e32 v148, v133
	v_mov_b32_e32 v149, v134
	v_mov_b32_e32 v133, v135
.LBB0_640:
	s_or_b64 exec, exec, s[0:1]
	v_pk_add_f32 v[132:133], v[148:149], v[132:133]
	v_or_b32_e32 v148, 16, v146
	v_add_f32_e32 v131, v132, v133
	v_and_b32_e32 v133, 64, v241
	v_xor_b32_e32 v132, 16, v241
	v_add_u32_e32 v133, 64, v133
	v_cmp_lt_i32_e32 vcc, v132, v133
	v_ashrrev_i32_e32 v149, 31, v148
	v_mov_b32_e32 v134, 0
	v_cndmask_b32_e32 v132, v241, v132, vcc
	v_lshlrev_b32_e32 v167, 2, v132
	ds_bpermute_b32 v132, v167, v131
	v_mov_b32_e32 v135, 0
	s_waitcnt lgkmcnt(0)
	v_add_f32_e32 v166, v131, v132
	v_xor_b32_e32 v131, 32, v241
	v_cmp_lt_i32_e32 vcc, v131, v133
	s_nop 1
	v_cndmask_b32_e32 v131, v241, v131, vcc
	v_lshlrev_b32_e32 v165, 2, v131
	ds_bpermute_b32 v170, v165, v166
	v_mov_b32_e32 v131, 0
	s_and_saveexec_b64 s[0:1], s[44:45]
	s_cbranch_execz .LBB0_642
	v_lshlrev_b64 v[130:131], 5, v[148:149]
	v_lshl_add_u64 v[130:131], v[144:145], 0, v[130:131]
	s_waitcnt vmcnt(6)
	v_mov_b32_e32 v130, v198
	v_mov_b32_e32 v131, v199
	v_mov_b32_e32 v132, v200
	v_mov_b32_e32 v133, v201
	v_mov_b32_e32 v134, v131
	v_mov_b32_e32 v135, v132
	v_mov_b32_e32 v131, v133
.LBB0_642:
	s_or_b64 exec, exec, s[0:1]
	v_pk_add_f32 v[130:131], v[134:135], v[130:131]
	v_or_b32_e32 v150, 32, v146
	v_add_f32_e32 v131, v130, v131
	ds_bpermute_b32 v132, v167, v131
	v_mov_b32_e32 v130, 0
	v_ashrrev_i32_e32 v151, 31, v150
	v_mov_b32_e32 v152, 0
	v_mov_b32_e32 v153, 0
	s_waitcnt lgkmcnt(0)
	v_add_f32_e32 v164, v131, v132
	ds_bpermute_b32 v171, v165, v164
	v_mov_b32_e32 v132, 0
	v_mov_b32_e32 v133, 0
	s_and_saveexec_b64 s[0:1], s[44:45]
	v_readlane_b32 s58, v254, 8
	v_readlane_b32 s30, v251, 4
	v_readlane_b32 s59, v254, 9
	v_readlane_b32 s31, v251, 5
	s_cbranch_execz .LBB0_644
	v_lshlrev_b64 v[132:133], 5, v[150:151]
	v_lshl_add_u64 v[132:133], v[144:145], 0, v[132:133]
	s_waitcnt vmcnt(5)
	v_mov_b32_e32 v132, v206
	v_mov_b32_e32 v133, v207
	v_mov_b32_e32 v134, v208
	v_mov_b32_e32 v135, v209
	v_mov_b32_e32 v152, v133
	v_mov_b32_e32 v153, v134
	v_mov_b32_e32 v133, v135
; __device__ __forceinline__ float row_ssq(const float* part, int pitch, int n4, int row, int fq) {
;     f32x4 v = (f32x4){0.f, 0.f, 0.f, 0.f};
;     if (fq < n4) v = *(const f32x4*)(part + (size_t)row * pitch + 4 * fq);
;     float s = (v[0] + v[1]) + (v[2] + v[3]);
;     s += __shfl_xor(s, 16); s += __shfl_xor(s, 32);
;     return s;
; }
;     __device__ __forceinline__ void operator()(const f32x4 (&acc)[2][2][4][2], const Unit& u, int wr, int wc, int fr, int fq) const {
;         const int row0 = u.pm * BM + wr * 64 + fr;
;         float rsv[2][4];
; #pragma unroll
;         for (int ai = 0; ai < 2; ++ai)
; #pragma unroll
;             for (int m = 0; m < 4; ++m) rsv[ai][m] = ssq_in ? rsqrtf(row_ssq(ssq_in, in_pitch, in_n4, row0 + ai * HALF + m * 16, fq) * inv_k + EPS) : 1.f;
.LBB0_644:
	s_or_b64 exec, exec, s[0:1]
	v_pk_add_f32 v[132:133], v[152:153], v[132:133]
	v_or_b32_e32 v152, 48, v146
	v_add_f32_e32 v131, v132, v133
	ds_bpermute_b32 v132, v167, v131
	v_ashrrev_i32_e32 v153, 31, v152
	v_mov_b32_e32 v134, 0
	v_mov_b32_e32 v135, 0
	s_waitcnt lgkmcnt(0)
	v_add_f32_e32 v162, v131, v132
	ds_bpermute_b32 v172, v165, v162
	v_mov_b32_e32 v131, 0
	s_and_saveexec_b64 s[0:1], s[44:45]
	s_cbranch_execz .LBB0_646
	v_lshlrev_b64 v[130:131], 5, v[152:153]
	v_lshl_add_u64 v[130:131], v[144:145], 0, v[130:131]
	s_waitcnt vmcnt(4)
	v_mov_b32_e32 v130, v210
	v_mov_b32_e32 v131, v211
	v_mov_b32_e32 v132, v212
	v_mov_b32_e32 v133, v213
	v_mov_b32_e32 v134, v131
	v_mov_b32_e32 v135, v132
	v_mov_b32_e32 v131, v133
.LBB0_646:
	s_or_b64 exec, exec, s[0:1]
	v_pk_add_f32 v[130:131], v[134:135], v[130:131]
	v_add_u32_e32 v154, 0x80, v146
	v_add_f32_e32 v131, v130, v131
	ds_bpermute_b32 v132, v167, v131
	v_mov_b32_e32 v130, 0
	v_ashrrev_i32_e32 v155, 31, v154
	v_mov_b32_e32 v156, 0
	v_mov_b32_e32 v157, 0
	s_waitcnt lgkmcnt(0)
	v_add_f32_e32 v160, v131, v132
	ds_bpermute_b32 v173, v165, v160
	v_mov_b32_e32 v132, 0
	v_mov_b32_e32 v133, 0
	s_and_saveexec_b64 s[0:1], s[44:45]
	s_cbranch_execz .LBB0_648
	v_lshlrev_b64 v[132:133], 5, v[154:155]
	v_lshl_add_u64 v[132:133], v[144:145], 0, v[132:133]
	s_waitcnt vmcnt(3)
	v_mov_b32_e32 v132, v214
	v_mov_b32_e32 v133, v215
	v_mov_b32_e32 v134, v216
	v_mov_b32_e32 v135, v217
	v_mov_b32_e32 v156, v133
	v_mov_b32_e32 v157, v134
	v_mov_b32_e32 v133, v135
.LBB0_648:
	s_or_b64 exec, exec, s[0:1]
	v_pk_add_f32 v[132:133], v[156:157], v[132:133]
	v_mov_b32_e32 v134, 0
	v_add_f32_e32 v131, v132, v133
	ds_bpermute_b32 v132, v167, v131
	v_mov_b32_e32 v135, 0
	s_waitcnt lgkmcnt(0)
	v_add_f32_e32 v158, v131, v132
	ds_bpermute_b32 v174, v165, v158
	v_mov_b32_e32 v131, 0
	s_and_saveexec_b64 s[0:1], s[44:45]
	s_cbranch_execz .LBB0_650
	v_lshlrev_b64 v[130:131], 5, v[146:147]
	v_lshl_add_u64 v[130:131], v[144:145], 0, v[130:131]
	v_add_co_u32_e32 v130, vcc, 0x1000, v130
	s_nop 1
	v_addc_co_u32_e32 v131, vcc, 0, v131, vcc
	s_waitcnt vmcnt(2)
	v_mov_b32_e32 v130, v218
	v_mov_b32_e32 v131, v219
	v_mov_b32_e32 v132, v220
	v_mov_b32_e32 v133, v221
	v_mov_b32_e32 v134, v131
	v_mov_b32_e32 v135, v132
	v_mov_b32_e32 v131, v133
.LBB0_650:
	s_or_b64 exec, exec, s[0:1]
	v_pk_add_f32 v[130:131], v[134:135], v[130:131]
	v_mov_b32_e32 v132, 0
	v_add_f32_e32 v130, v130, v131
	ds_bpermute_b32 v131, v167, v130
	v_mov_b32_e32 v156, 0
	v_mov_b32_e32 v157, 0
	v_mov_b32_e32 v133, 0
	s_waitcnt lgkmcnt(0)
	v_add_f32_e32 v175, v130, v131
	ds_bpermute_b32 v176, v165, v175
	v_mov_b32_e32 v130, 0
	s_and_saveexec_b64 s[0:1], s[44:45]
	s_cbranch_execz .LBB0_652
	v_lshlrev_b64 v[132:133], 5, v[146:147]
	v_lshl_add_u64 v[132:133], v[144:145], 0, v[132:133]
	v_add_co_u32_e32 v132, vcc, 0x1000, v132
	s_nop 1
	v_addc_co_u32_e32 v133, vcc, 0, v133, vcc
	s_waitcnt vmcnt(1)
	v_mov_b32_e32 v132, v226
	v_mov_b32_e32 v133, v227
	v_mov_b32_e32 v134, v228
	v_mov_b32_e32 v135, v229
	v_mov_b32_e32 v156, v133
	v_mov_b32_e32 v157, v134
	v_mov_b32_e32 v133, v135
.LBB0_652:
	s_or_b64 exec, exec, s[0:1]
	v_pk_add_f32 v[132:133], v[156:157], v[132:133]
	v_add_u32_e32 v156, 0xb0, v146
	v_add_f32_e32 v131, v132, v133
	ds_bpermute_b32 v132, v167, v131
	v_ashrrev_i32_e32 v157, 31, v156
	v_mov_b32_e32 v168, 0
	v_mov_b32_e32 v169, 0
	s_waitcnt lgkmcnt(0)
	v_add_f32_e32 v134, v131, v132
	ds_bpermute_b32 v135, v165, v134
	v_mov_b32_e32 v131, 0
	s_and_saveexec_b64 s[0:1], s[44:45]
	s_cbranch_execz .LBB0_654
	v_lshlrev_b64 v[130:131], 5, v[156:157]
	v_lshl_add_u64 v[130:131], v[144:145], 0, v[130:131]
	s_waitcnt vmcnt(0)
	v_mov_b32_e32 v130, v230
	v_mov_b32_e32 v131, v231
	v_mov_b32_e32 v132, v232
	v_mov_b32_e32 v133, v233
	v_mov_b32_e32 v168, v131
	v_mov_b32_e32 v169, v132
	v_mov_b32_e32 v131, v133
